# FFN gate/up GEMM epilogue rewritten by hand: packed f32 math, silu(g*r)*(u*r) as g*u*r^2/(1+exp2(-g*r*log2e)), staged exp/rcp, one base address; plus HGRN LDS-read pipelining
# speedup vs baseline: 1.0251x; 1.0251x over previous
; __device__ __forceinline__ unsigned pk2(float lo, float hi) { unsigned r; asm("v_cvt_pk_bf16_f32 %0, %1, %2" : "=v"(r) : "v"(lo), "v"(hi)); return r; }
; __device__ __forceinline__ float sigmoidf_(float v) { return __builtin_amdgcn_rcpf(1.0f + fexp(-v)); }
; __device__ __forceinline__ void row_rstd8(const ssq_t* ss, int row0, float (&r)[8]) {
;     ssq_t sv[8];
; #pragma unroll
;     for (int k = 0; k < 8; ++k) sv[k] = ss[row0 + (k >> 2) * 128 + (k & 3) * 16];
;     asm volatile("" ::: "memory");
; #pragma unroll
;     for (int k = 0; k < 8; ++k) r[k] = rsqrtf((float)sv[k] * (1.0f / SSQ_SCALE) * (1.0f / D) + EPS);
; }
; __device__ __forceinline__ float row_rstd(const ssq_t* ss, int row) { return rsqrtf((float)ss[row] * (1.0f / SSQ_SCALE) * (1.0f / D) + EPS); }
;     __device__ __forceinline__ bool operator()(f32x4 (&acc)[2][2][4][2], const pg8::Unit& u, int wr, int wc, int fr, int fq) const {
;         const int row0 = u.pm * 256 + wr * 64 + fr, col0 = u.pn * 128 + wc * 32 + 8 * fq;
;         float rr[8]; row_rstd8(ss, row0, rr);
; #pragma unroll
;         for (int ai = 0; ai < 2; ++ai)
; #pragma unroll
;             for (int m = 0; m < 4; ++m) {
;                 const int row = row0 + ai * 128 + m * 16; const float r = rr[ai * 4 + m];
;                 float o[8];
; #pragma unroll
;                 for (int n = 0; n < 2; ++n)
; #pragma unroll
;                     for (int j = 0; j < 4; ++j) { const float gv = acc[ai][0][m][n][j] * r, uv = acc[ai][1][m][n][j] * r; o[n * 4 + j] = gv * sigmoidf_(gv) * uv; }
;                 u32x4 w; w.x = pk2(o[0], o[1]); w.y = pk2(o[2], o[3]); w.z = pk2(o[4], o[5]); w.w = pk2(o[6], o[7]);
;                 *(u32x4*)(act + (size_t)row * FF + col0) = w;
.LBB0_97:
	v_lshl_add_u32 v140, s35, 8, v151
	v_readlane_b32 s6, v255, 31
	v_ashrrev_i32_e32 v141, 31, v140
	v_readlane_b32 s7, v255, 32
	v_lshl_or_b32 v156, s34, 7, v155
	v_ashrrev_i32_e32 v157, 31, v156
	v_lshl_add_u64 v[142:143], v[140:141], 3, s[6:7]
	global_load_dwordx2 v[160:161], v[142:143], off
	global_load_dwordx2 v[162:163], v[142:143], off offset:128
	global_load_dwordx2 v[164:165], v[142:143], off offset:256
	global_load_dwordx2 v[166:167], v[142:143], off offset:384
	global_load_dwordx2 v[146:147], v[142:143], off offset:1024
	global_load_dwordx2 v[148:149], v[142:143], off offset:1152
	global_load_dwordx2 v[144:145], v[142:143], off offset:1280
	s_nop 0
	global_load_dwordx2 v[142:143], v[142:143], off offset:1408
	v_lshlrev_b64 v[156:157], 1, v[156:157]
	v_lshl_add_u64 v[156:157], v[156:157], 0, s[90:91]
	v_mad_i64_i32 v[156:157], s[6:7], v140, s37, v[156:157]
	v_mov_b32_e32 v140, 1.0
	v_mov_b32_e32 v141, 1.0
	v_pk_mul_f32 v[122:123], v[122:123], v[126:127]
	v_pk_mul_f32 v[124:125], v[124:125], v[128:129]
	v_pk_mul_f32 v[114:115], v[114:115], v[118:119]
	v_pk_mul_f32 v[116:117], v[116:117], v[120:121]
	v_pk_mul_f32 v[106:107], v[106:107], v[110:111]
	v_pk_mul_f32 v[108:109], v[108:109], v[112:113]
	v_pk_mul_f32 v[98:99], v[98:99], v[102:103]
	v_pk_mul_f32 v[100:101], v[100:101], v[104:105]
	v_pk_mul_f32 v[90:91], v[90:91], v[94:95]
	v_pk_mul_f32 v[92:93], v[92:93], v[96:97]
	v_pk_mul_f32 v[82:83], v[82:83], v[86:87]
	v_pk_mul_f32 v[84:85], v[84:85], v[88:89]
	v_pk_mul_f32 v[74:75], v[74:75], v[78:79]
	v_pk_mul_f32 v[76:77], v[76:77], v[80:81]
	v_pk_mul_f32 v[66:67], v[66:67], v[70:71]
	v_pk_mul_f32 v[68:69], v[68:69], v[72:73]
	v_pk_mul_f32 v[58:59], v[58:59], v[62:63]
	v_pk_mul_f32 v[60:61], v[60:61], v[64:65]
	v_pk_mul_f32 v[50:51], v[50:51], v[54:55]
	v_pk_mul_f32 v[52:53], v[52:53], v[56:57]
	v_pk_mul_f32 v[42:43], v[42:43], v[46:47]
	v_pk_mul_f32 v[44:45], v[44:45], v[48:49]
	v_pk_mul_f32 v[34:35], v[34:35], v[38:39]
	v_pk_mul_f32 v[36:37], v[36:37], v[40:41]
	v_pk_mul_f32 v[26:27], v[26:27], v[30:31]
	v_pk_mul_f32 v[28:29], v[28:29], v[32:33]
	v_pk_mul_f32 v[18:19], v[18:19], v[22:23]
	v_pk_mul_f32 v[20:21], v[20:21], v[24:25]
	v_pk_mul_f32 v[10:11], v[10:11], v[14:15]
	v_pk_mul_f32 v[12:13], v[12:13], v[16:17]
	v_pk_mul_f32 v[2:3], v[2:3], v[6:7]
	v_pk_mul_f32 v[4:5], v[4:5], v[8:9]
	s_mov_b32 s6, 0x2c000
	s_mov_b32 s7, 0
	s_waitcnt vmcnt(0)
	v_ffbh_u32_e32 v150, v161
	v_min_u32_e32 v150, 32, v150
	v_lshlrev_b64 v[160:161], v150, v[160:161]
	v_min_u32_e32 v152, 1, v160
	v_or_b32_e32 v152, v161, v152
	v_cvt_f32_u32_e32 v152, v152
	v_sub_u32_e32 v150, 32, v150
	v_ldexp_f32 v152, v152, v150
	v_mul_f32_e32 v152, 0x33800000, v152
	v_fmamk_f32 v152, v152, 0x3a000000, v218
	v_rsq_f32_e32 v160, v152
	v_ffbh_u32_e32 v150, v163
	v_min_u32_e32 v150, 32, v150
	v_lshlrev_b64 v[162:163], v150, v[162:163]
	v_min_u32_e32 v152, 1, v162
	v_or_b32_e32 v152, v163, v152
	v_cvt_f32_u32_e32 v152, v152
	v_sub_u32_e32 v150, 32, v150
	v_ldexp_f32 v152, v152, v150
	v_mul_f32_e32 v152, 0x33800000, v152
	v_fmamk_f32 v152, v152, 0x3a000000, v218
	v_rsq_f32_e32 v162, v152
	v_ffbh_u32_e32 v150, v165
	v_min_u32_e32 v150, 32, v150
	v_lshlrev_b64 v[164:165], v150, v[164:165]
	v_min_u32_e32 v152, 1, v164
	v_or_b32_e32 v152, v165, v152
	v_cvt_f32_u32_e32 v152, v152
	v_sub_u32_e32 v150, 32, v150
	v_ldexp_f32 v152, v152, v150
	v_mul_f32_e32 v152, 0x33800000, v152
	v_fmamk_f32 v152, v152, 0x3a000000, v218
	v_rsq_f32_e32 v164, v152
	v_ffbh_u32_e32 v150, v167
	v_min_u32_e32 v150, 32, v150
	v_lshlrev_b64 v[166:167], v150, v[166:167]
	v_min_u32_e32 v152, 1, v166
	v_or_b32_e32 v152, v167, v152
	v_cvt_f32_u32_e32 v152, v152
	v_sub_u32_e32 v150, 32, v150
	v_ldexp_f32 v152, v152, v150
	v_mul_f32_e32 v152, 0x33800000, v152
	v_fmamk_f32 v152, v152, 0x3a000000, v218
	v_rsq_f32_e32 v166, v152
	v_ffbh_u32_e32 v150, v147
	v_min_u32_e32 v150, 32, v150
	v_lshlrev_b64 v[146:147], v150, v[146:147]
	v_min_u32_e32 v152, 1, v146
	v_or_b32_e32 v152, v147, v152
	v_cvt_f32_u32_e32 v152, v152
	v_sub_u32_e32 v150, 32, v150
	v_ldexp_f32 v152, v152, v150
	v_mul_f32_e32 v152, 0x33800000, v152
	v_fmamk_f32 v152, v152, 0x3a000000, v218
	v_rsq_f32_e32 v146, v152
	v_ffbh_u32_e32 v150, v149
	v_min_u32_e32 v150, 32, v150
	v_lshlrev_b64 v[148:149], v150, v[148:149]
	v_min_u32_e32 v152, 1, v148
	v_or_b32_e32 v152, v149, v152
	v_cvt_f32_u32_e32 v152, v152
	v_sub_u32_e32 v150, 32, v150
	v_ldexp_f32 v152, v152, v150
	v_mul_f32_e32 v152, 0x33800000, v152
	v_fmamk_f32 v152, v152, 0x3a000000, v218
	v_rsq_f32_e32 v148, v152
	v_ffbh_u32_e32 v150, v145
	v_min_u32_e32 v150, 32, v150
	v_lshlrev_b64 v[144:145], v150, v[144:145]
	v_min_u32_e32 v152, 1, v144
	v_or_b32_e32 v152, v145, v152
	v_cvt_f32_u32_e32 v152, v152
	v_sub_u32_e32 v150, 32, v150
	v_ldexp_f32 v152, v152, v150
	v_mul_f32_e32 v152, 0x33800000, v152
	v_fmamk_f32 v152, v152, 0x3a000000, v218
	v_rsq_f32_e32 v144, v152
	v_ffbh_u32_e32 v150, v143
	v_min_u32_e32 v150, 32, v150
	v_lshlrev_b64 v[142:143], v150, v[142:143]
	v_min_u32_e32 v152, 1, v142
	v_or_b32_e32 v152, v143, v152
	v_cvt_f32_u32_e32 v152, v152
	v_sub_u32_e32 v150, 32, v150
	v_ldexp_f32 v152, v152, v150
	v_mul_f32_e32 v152, 0x33800000, v152
	v_fmamk_f32 v152, v152, 0x3a000000, v218
	v_rsq_f32_e32 v142, v152
	s_nop 0
	v_mul_f32_e32 v150, 0xbfb8aa3b, v160
	v_mul_f32_e32 v152, v160, v160
	v_pk_mul_f32 v[126:127], v[126:127], v[150:151] op_sel_hi:[1,0]
	v_pk_mul_f32 v[128:129], v[128:129], v[150:151] op_sel_hi:[1,0]
	v_pk_mul_f32 v[118:119], v[118:119], v[150:151] op_sel_hi:[1,0]
	v_pk_mul_f32 v[120:121], v[120:121], v[150:151] op_sel_hi:[1,0]
	v_exp_f32_e32 v126, v126
	v_exp_f32_e32 v127, v127
; __device__ __forceinline__ unsigned pk2(float lo, float hi) { unsigned r; asm("v_cvt_pk_bf16_f32 %0, %1, %2" : "=v"(r) : "v"(lo), "v"(hi)); return r; }
; __device__ __forceinline__ float sigmoidf_(float v) { return __builtin_amdgcn_rcpf(1.0f + fexp(-v)); }
;     __device__ __forceinline__ bool operator()(f32x4 (&acc)[2][2][4][2], const pg8::Unit& u, int wr, int wc, int fr, int fq) const {
;     ...
;                 const int row = row0 + ai * 128 + m * 16; const float r = rr[ai * 4 + m];
;                 float o[8];
; #pragma unroll
;                 for (int n = 0; n < 2; ++n)
; #pragma unroll
;                     for (int j = 0; j < 4; ++j) { const float gv = acc[ai][0][m][n][j] * r, uv = acc[ai][1][m][n][j] * r; o[n * 4 + j] = gv * sigmoidf_(gv) * uv; }
;                 u32x4 w; w.x = pk2(o[0], o[1]); w.y = pk2(o[2], o[3]); w.z = pk2(o[4], o[5]); w.w = pk2(o[6], o[7]);
;                 *(u32x4*)(act + (size_t)row * FF + col0) = w;
	v_exp_f32_e32 v128, v128
	v_exp_f32_e32 v129, v129
	v_exp_f32_e32 v118, v118
	v_exp_f32_e32 v119, v119
	v_exp_f32_e32 v120, v120
	v_exp_f32_e32 v121, v121
	v_pk_mul_f32 v[122:123], v[122:123], v[152:153] op_sel_hi:[1,0]
	v_pk_mul_f32 v[124:125], v[124:125], v[152:153] op_sel_hi:[1,0]
	v_pk_mul_f32 v[114:115], v[114:115], v[152:153] op_sel_hi:[1,0]
	v_pk_mul_f32 v[116:117], v[116:117], v[152:153] op_sel_hi:[1,0]
	v_pk_add_f32 v[126:127], v[126:127], v[140:141]
	v_pk_add_f32 v[128:129], v[128:129], v[140:141]
	v_pk_add_f32 v[118:119], v[118:119], v[140:141]
	v_pk_add_f32 v[120:121], v[120:121], v[140:141]
	v_rcp_f32_e32 v126, v126
	v_rcp_f32_e32 v127, v127
	v_rcp_f32_e32 v128, v128
	v_rcp_f32_e32 v129, v129
	v_rcp_f32_e32 v118, v118
	v_rcp_f32_e32 v119, v119
	v_rcp_f32_e32 v120, v120
	v_rcp_f32_e32 v121, v121
	s_nop 0
	v_pk_mul_f32 v[122:123], v[122:123], v[126:127]
	v_pk_mul_f32 v[124:125], v[124:125], v[128:129]
	v_pk_mul_f32 v[114:115], v[114:115], v[118:119]
	v_pk_mul_f32 v[116:117], v[116:117], v[120:121]
	v_cvt_pk_bf16_f32 v126, v122, v123
	v_cvt_pk_bf16_f32 v127, v124, v125
	v_cvt_pk_bf16_f32 v128, v114, v115
	v_cvt_pk_bf16_f32 v129, v116, v117
	global_store_dwordx4 v[156:157], v[126:129], off
	v_lshl_add_u64 v[156:157], v[156:157], 0, s[6:7]
	v_mul_f32_e32 v150, 0xbfb8aa3b, v162
	v_mul_f32_e32 v152, v162, v162
	v_pk_mul_f32 v[110:111], v[110:111], v[150:151] op_sel_hi:[1,0]
	v_pk_mul_f32 v[112:113], v[112:113], v[150:151] op_sel_hi:[1,0]
	v_pk_mul_f32 v[102:103], v[102:103], v[150:151] op_sel_hi:[1,0]
	v_pk_mul_f32 v[104:105], v[104:105], v[150:151] op_sel_hi:[1,0]
	v_exp_f32_e32 v110, v110
	v_exp_f32_e32 v111, v111
	v_exp_f32_e32 v112, v112
	v_exp_f32_e32 v113, v113
	v_exp_f32_e32 v102, v102
	v_exp_f32_e32 v103, v103
	v_exp_f32_e32 v104, v104
	v_exp_f32_e32 v105, v105
	v_pk_mul_f32 v[106:107], v[106:107], v[152:153] op_sel_hi:[1,0]
	v_pk_mul_f32 v[108:109], v[108:109], v[152:153] op_sel_hi:[1,0]
	v_pk_mul_f32 v[98:99], v[98:99], v[152:153] op_sel_hi:[1,0]
	v_pk_mul_f32 v[100:101], v[100:101], v[152:153] op_sel_hi:[1,0]
	v_pk_add_f32 v[110:111], v[110:111], v[140:141]
	v_pk_add_f32 v[112:113], v[112:113], v[140:141]
	v_pk_add_f32 v[102:103], v[102:103], v[140:141]
	v_pk_add_f32 v[104:105], v[104:105], v[140:141]
	v_rcp_f32_e32 v110, v110
	v_rcp_f32_e32 v111, v111
	v_rcp_f32_e32 v112, v112
	v_rcp_f32_e32 v113, v113
	v_rcp_f32_e32 v102, v102
	v_rcp_f32_e32 v103, v103
	v_rcp_f32_e32 v104, v104
	v_rcp_f32_e32 v105, v105
	s_nop 0
	v_pk_mul_f32 v[106:107], v[106:107], v[110:111]
	v_pk_mul_f32 v[108:109], v[108:109], v[112:113]
	v_pk_mul_f32 v[98:99], v[98:99], v[102:103]
	v_pk_mul_f32 v[100:101], v[100:101], v[104:105]
	v_cvt_pk_bf16_f32 v110, v106, v107
	v_cvt_pk_bf16_f32 v111, v108, v109
	v_cvt_pk_bf16_f32 v112, v98, v99
	v_cvt_pk_bf16_f32 v113, v100, v101
	global_store_dwordx4 v[156:157], v[110:113], off
	v_lshl_add_u64 v[156:157], v[156:157], 0, s[6:7]
	v_mul_f32_e32 v150, 0xbfb8aa3b, v164
	v_mul_f32_e32 v152, v164, v164
	v_pk_mul_f32 v[94:95], v[94:95], v[150:151] op_sel_hi:[1,0]
	v_pk_mul_f32 v[96:97], v[96:97], v[150:151] op_sel_hi:[1,0]
	v_pk_mul_f32 v[86:87], v[86:87], v[150:151] op_sel_hi:[1,0]
	v_pk_mul_f32 v[88:89], v[88:89], v[150:151] op_sel_hi:[1,0]
	v_exp_f32_e32 v94, v94
	v_exp_f32_e32 v95, v95
	v_exp_f32_e32 v96, v96
	v_exp_f32_e32 v97, v97
	v_exp_f32_e32 v86, v86
	v_exp_f32_e32 v87, v87
	v_exp_f32_e32 v88, v88
	v_exp_f32_e32 v89, v89
	v_pk_mul_f32 v[90:91], v[90:91], v[152:153] op_sel_hi:[1,0]
	v_pk_mul_f32 v[92:93], v[92:93], v[152:153] op_sel_hi:[1,0]
	v_pk_mul_f32 v[82:83], v[82:83], v[152:153] op_sel_hi:[1,0]
	v_pk_mul_f32 v[84:85], v[84:85], v[152:153] op_sel_hi:[1,0]
	v_pk_add_f32 v[94:95], v[94:95], v[140:141]
	v_pk_add_f32 v[96:97], v[96:97], v[140:141]
	v_pk_add_f32 v[86:87], v[86:87], v[140:141]
	v_pk_add_f32 v[88:89], v[88:89], v[140:141]
	v_rcp_f32_e32 v94, v94
	v_rcp_f32_e32 v95, v95
	v_rcp_f32_e32 v96, v96
	v_rcp_f32_e32 v97, v97
	v_rcp_f32_e32 v86, v86
	v_rcp_f32_e32 v87, v87
	v_rcp_f32_e32 v88, v88
	v_rcp_f32_e32 v89, v89
	s_nop 0
	v_pk_mul_f32 v[90:91], v[90:91], v[94:95]
	v_pk_mul_f32 v[92:93], v[92:93], v[96:97]
	v_pk_mul_f32 v[82:83], v[82:83], v[86:87]
	v_pk_mul_f32 v[84:85], v[84:85], v[88:89]
	v_cvt_pk_bf16_f32 v94, v90, v91
	v_cvt_pk_bf16_f32 v95, v92, v93
	v_cvt_pk_bf16_f32 v96, v82, v83
	v_cvt_pk_bf16_f32 v97, v84, v85
	global_store_dwordx4 v[156:157], v[94:97], off
	v_lshl_add_u64 v[156:157], v[156:157], 0, s[6:7]
	v_mul_f32_e32 v150, 0xbfb8aa3b, v166
	v_mul_f32_e32 v152, v166, v166
	v_pk_mul_f32 v[78:79], v[78:79], v[150:151] op_sel_hi:[1,0]
	v_pk_mul_f32 v[80:81], v[80:81], v[150:151] op_sel_hi:[1,0]
	v_pk_mul_f32 v[70:71], v[70:71], v[150:151] op_sel_hi:[1,0]
	v_pk_mul_f32 v[72:73], v[72:73], v[150:151] op_sel_hi:[1,0]
	v_exp_f32_e32 v78, v78
	v_exp_f32_e32 v79, v79
	v_exp_f32_e32 v80, v80
	v_exp_f32_e32 v81, v81
	v_exp_f32_e32 v70, v70
	v_exp_f32_e32 v71, v71
	v_exp_f32_e32 v72, v72
	v_exp_f32_e32 v73, v73
	v_pk_mul_f32 v[74:75], v[74:75], v[152:153] op_sel_hi:[1,0]
	v_pk_mul_f32 v[76:77], v[76:77], v[152:153] op_sel_hi:[1,0]
	v_pk_mul_f32 v[66:67], v[66:67], v[152:153] op_sel_hi:[1,0]
	v_pk_mul_f32 v[68:69], v[68:69], v[152:153] op_sel_hi:[1,0]
	v_pk_add_f32 v[78:79], v[78:79], v[140:141]
	v_pk_add_f32 v[80:81], v[80:81], v[140:141]
	v_pk_add_f32 v[70:71], v[70:71], v[140:141]
	v_pk_add_f32 v[72:73], v[72:73], v[140:141]
	v_rcp_f32_e32 v78, v78
	v_rcp_f32_e32 v79, v79
	v_rcp_f32_e32 v80, v80
	v_rcp_f32_e32 v81, v81
	v_rcp_f32_e32 v70, v70
	v_rcp_f32_e32 v71, v71
	v_rcp_f32_e32 v72, v72
	v_rcp_f32_e32 v73, v73
	s_nop 0
	v_pk_mul_f32 v[74:75], v[74:75], v[78:79]
	v_pk_mul_f32 v[76:77], v[76:77], v[80:81]
; __device__ __forceinline__ unsigned pk2(float lo, float hi) { unsigned r; asm("v_cvt_pk_bf16_f32 %0, %1, %2" : "=v"(r) : "v"(lo), "v"(hi)); return r; }
; __device__ __forceinline__ float sigmoidf_(float v) { return __builtin_amdgcn_rcpf(1.0f + fexp(-v)); }
; #define PG8_BAR __builtin_amdgcn_s_barrier()
; template <class Epi, class Sched, bool ALIGN_EPI = true, bool SP2 = true>
; __device__ __forceinline__ void gemm_phase(LAS unsigned char* lds, const Gemm g, const Sched& S, const Epi& E) {
;     ...
;         if (!has_next) break;
;         if (!keep) {
; #pragma unroll
;         for (int a = 0; a < 2; ++a)
; #pragma unroll
;             for (int b = 0; b < 2; ++b)
; #pragma unroll
;                 for (int m = 0; m < 4; ++m)
; #pragma unroll
;                     for (int n = 0; n < 2; ++n) acc[a][b][m][n] = (f32x4){0.f, 0.f, 0.f, 0.f};
;         }
;         cur = nxt; cA = nA; cB = nB; ++ui;
;         if constexpr (ALIGN_EPI) { if (wr == 1) PG8_BAR; }
;     __device__ __forceinline__ bool operator()(f32x4 (&acc)[2][2][4][2], const pg8::Unit& u, int wr, int wc, int fr, int fq) const {
;     ...
;             for (int m = 0; m < 4; ++m) {
;                 const int row = row0 + ai * 128 + m * 16; const float r = rr[ai * 4 + m];
;                 float o[8];
; #pragma unroll
;                 for (int n = 0; n < 2; ++n)
; #pragma unroll
;                     for (int j = 0; j < 4; ++j) { const float gv = acc[ai][0][m][n][j] * r, uv = acc[ai][1][m][n][j] * r; o[n * 4 + j] = gv * sigmoidf_(gv) * uv; }
;                 u32x4 w; w.x = pk2(o[0], o[1]); w.y = pk2(o[2], o[3]); w.z = pk2(o[4], o[5]); w.w = pk2(o[6], o[7]);
;                 *(u32x4*)(act + (size_t)row * FF + col0) = w;
;             }
;         return false;
	v_pk_mul_f32 v[66:67], v[66:67], v[70:71]
	v_pk_mul_f32 v[68:69], v[68:69], v[72:73]
	v_cvt_pk_bf16_f32 v78, v74, v75
	v_cvt_pk_bf16_f32 v79, v76, v77
	v_cvt_pk_bf16_f32 v80, v66, v67
	v_cvt_pk_bf16_f32 v81, v68, v69
	global_store_dwordx4 v[156:157], v[78:81], off
	s_mov_b32 s6, 0xdc000
	v_lshl_add_u64 v[156:157], v[156:157], 0, s[6:7]
	s_mov_b32 s6, 0x2c000
	v_mul_f32_e32 v150, 0xbfb8aa3b, v146
	v_mul_f32_e32 v152, v146, v146
	v_pk_mul_f32 v[62:63], v[62:63], v[150:151] op_sel_hi:[1,0]
	v_pk_mul_f32 v[64:65], v[64:65], v[150:151] op_sel_hi:[1,0]
	v_pk_mul_f32 v[54:55], v[54:55], v[150:151] op_sel_hi:[1,0]
	v_pk_mul_f32 v[56:57], v[56:57], v[150:151] op_sel_hi:[1,0]
	v_exp_f32_e32 v62, v62
	v_exp_f32_e32 v63, v63
	v_exp_f32_e32 v64, v64
	v_exp_f32_e32 v65, v65
	v_exp_f32_e32 v54, v54
	v_exp_f32_e32 v55, v55
	v_exp_f32_e32 v56, v56
	v_exp_f32_e32 v57, v57
	v_pk_mul_f32 v[58:59], v[58:59], v[152:153] op_sel_hi:[1,0]
	v_pk_mul_f32 v[60:61], v[60:61], v[152:153] op_sel_hi:[1,0]
	v_pk_mul_f32 v[50:51], v[50:51], v[152:153] op_sel_hi:[1,0]
	v_pk_mul_f32 v[52:53], v[52:53], v[152:153] op_sel_hi:[1,0]
	v_pk_add_f32 v[62:63], v[62:63], v[140:141]
	v_pk_add_f32 v[64:65], v[64:65], v[140:141]
	v_pk_add_f32 v[54:55], v[54:55], v[140:141]
	v_pk_add_f32 v[56:57], v[56:57], v[140:141]
	v_rcp_f32_e32 v62, v62
	v_rcp_f32_e32 v63, v63
	v_rcp_f32_e32 v64, v64
	v_rcp_f32_e32 v65, v65
	v_rcp_f32_e32 v54, v54
	v_rcp_f32_e32 v55, v55
	v_rcp_f32_e32 v56, v56
	v_rcp_f32_e32 v57, v57
	s_nop 0
	v_pk_mul_f32 v[58:59], v[58:59], v[62:63]
	v_pk_mul_f32 v[60:61], v[60:61], v[64:65]
	v_pk_mul_f32 v[50:51], v[50:51], v[54:55]
	v_pk_mul_f32 v[52:53], v[52:53], v[56:57]
	v_cvt_pk_bf16_f32 v62, v58, v59
	v_cvt_pk_bf16_f32 v63, v60, v61
	v_cvt_pk_bf16_f32 v64, v50, v51
	v_cvt_pk_bf16_f32 v65, v52, v53
	global_store_dwordx4 v[156:157], v[62:65], off
	v_lshl_add_u64 v[156:157], v[156:157], 0, s[6:7]
	v_mul_f32_e32 v150, 0xbfb8aa3b, v148
	v_mul_f32_e32 v152, v148, v148
	v_pk_mul_f32 v[46:47], v[46:47], v[150:151] op_sel_hi:[1,0]
	v_pk_mul_f32 v[48:49], v[48:49], v[150:151] op_sel_hi:[1,0]
	v_pk_mul_f32 v[38:39], v[38:39], v[150:151] op_sel_hi:[1,0]
	v_pk_mul_f32 v[40:41], v[40:41], v[150:151] op_sel_hi:[1,0]
	v_exp_f32_e32 v46, v46
	v_exp_f32_e32 v47, v47
	v_exp_f32_e32 v48, v48
	v_exp_f32_e32 v49, v49
	v_exp_f32_e32 v38, v38
	v_exp_f32_e32 v39, v39
	v_exp_f32_e32 v40, v40
	v_exp_f32_e32 v41, v41
	v_pk_mul_f32 v[42:43], v[42:43], v[152:153] op_sel_hi:[1,0]
	v_pk_mul_f32 v[44:45], v[44:45], v[152:153] op_sel_hi:[1,0]
	v_pk_mul_f32 v[34:35], v[34:35], v[152:153] op_sel_hi:[1,0]
	v_pk_mul_f32 v[36:37], v[36:37], v[152:153] op_sel_hi:[1,0]
	v_pk_add_f32 v[46:47], v[46:47], v[140:141]
	v_pk_add_f32 v[48:49], v[48:49], v[140:141]
	v_pk_add_f32 v[38:39], v[38:39], v[140:141]
	v_pk_add_f32 v[40:41], v[40:41], v[140:141]
	v_rcp_f32_e32 v46, v46
	v_rcp_f32_e32 v47, v47
	v_rcp_f32_e32 v48, v48
	v_rcp_f32_e32 v49, v49
	v_rcp_f32_e32 v38, v38
	v_rcp_f32_e32 v39, v39
	v_rcp_f32_e32 v40, v40
	v_rcp_f32_e32 v41, v41
	s_nop 0
	v_pk_mul_f32 v[42:43], v[42:43], v[46:47]
	v_pk_mul_f32 v[44:45], v[44:45], v[48:49]
	v_pk_mul_f32 v[34:35], v[34:35], v[38:39]
	v_pk_mul_f32 v[36:37], v[36:37], v[40:41]
	v_cvt_pk_bf16_f32 v46, v42, v43
	v_cvt_pk_bf16_f32 v47, v44, v45
	v_cvt_pk_bf16_f32 v48, v34, v35
	v_cvt_pk_bf16_f32 v49, v36, v37
	global_store_dwordx4 v[156:157], v[46:49], off
	v_lshl_add_u64 v[156:157], v[156:157], 0, s[6:7]
	v_mul_f32_e32 v150, 0xbfb8aa3b, v144
	v_mul_f32_e32 v152, v144, v144
	v_pk_mul_f32 v[30:31], v[30:31], v[150:151] op_sel_hi:[1,0]
	v_pk_mul_f32 v[32:33], v[32:33], v[150:151] op_sel_hi:[1,0]
	v_pk_mul_f32 v[22:23], v[22:23], v[150:151] op_sel_hi:[1,0]
	v_pk_mul_f32 v[24:25], v[24:25], v[150:151] op_sel_hi:[1,0]
	v_exp_f32_e32 v30, v30
	v_exp_f32_e32 v31, v31
	v_exp_f32_e32 v32, v32
	v_exp_f32_e32 v33, v33
	v_exp_f32_e32 v22, v22
	v_exp_f32_e32 v23, v23
	v_exp_f32_e32 v24, v24
	v_exp_f32_e32 v25, v25
	v_pk_mul_f32 v[26:27], v[26:27], v[152:153] op_sel_hi:[1,0]
	v_pk_mul_f32 v[28:29], v[28:29], v[152:153] op_sel_hi:[1,0]
	v_pk_mul_f32 v[18:19], v[18:19], v[152:153] op_sel_hi:[1,0]
	v_pk_mul_f32 v[20:21], v[20:21], v[152:153] op_sel_hi:[1,0]
	v_pk_add_f32 v[30:31], v[30:31], v[140:141]
	v_pk_add_f32 v[32:33], v[32:33], v[140:141]
	v_pk_add_f32 v[22:23], v[22:23], v[140:141]
	v_pk_add_f32 v[24:25], v[24:25], v[140:141]
	v_rcp_f32_e32 v30, v30
	v_rcp_f32_e32 v31, v31
	v_rcp_f32_e32 v32, v32
	v_rcp_f32_e32 v33, v33
	v_rcp_f32_e32 v22, v22
	v_rcp_f32_e32 v23, v23
	v_rcp_f32_e32 v24, v24
	v_rcp_f32_e32 v25, v25
	s_nop 0
	v_pk_mul_f32 v[26:27], v[26:27], v[30:31]
	v_pk_mul_f32 v[28:29], v[28:29], v[32:33]
	v_pk_mul_f32 v[18:19], v[18:19], v[22:23]
	v_pk_mul_f32 v[20:21], v[20:21], v[24:25]
	v_cvt_pk_bf16_f32 v30, v26, v27
	v_cvt_pk_bf16_f32 v31, v28, v29
	v_cvt_pk_bf16_f32 v32, v18, v19
	v_cvt_pk_bf16_f32 v33, v20, v21
	global_store_dwordx4 v[156:157], v[30:33], off
	v_lshl_add_u64 v[156:157], v[156:157], 0, s[6:7]
	v_mul_f32_e32 v150, 0xbfb8aa3b, v142
	v_mul_f32_e32 v152, v142, v142
	v_pk_mul_f32 v[14:15], v[14:15], v[150:151] op_sel_hi:[1,0]
	v_pk_mul_f32 v[16:17], v[16:17], v[150:151] op_sel_hi:[1,0]
	v_pk_mul_f32 v[6:7], v[6:7], v[150:151] op_sel_hi:[1,0]
	v_pk_mul_f32 v[8:9], v[8:9], v[150:151] op_sel_hi:[1,0]
	v_exp_f32_e32 v14, v14
	v_exp_f32_e32 v15, v15
	v_exp_f32_e32 v16, v16
	v_exp_f32_e32 v17, v17
	v_exp_f32_e32 v6, v6
	v_exp_f32_e32 v7, v7
	v_exp_f32_e32 v8, v8
	v_exp_f32_e32 v9, v9
	v_pk_mul_f32 v[10:11], v[10:11], v[152:153] op_sel_hi:[1,0]
	v_pk_mul_f32 v[12:13], v[12:13], v[152:153] op_sel_hi:[1,0]
	v_pk_mul_f32 v[2:3], v[2:3], v[152:153] op_sel_hi:[1,0]
	v_pk_mul_f32 v[4:5], v[4:5], v[152:153] op_sel_hi:[1,0]
	v_pk_add_f32 v[14:15], v[14:15], v[140:141]
	v_pk_add_f32 v[16:17], v[16:17], v[140:141]
	v_pk_add_f32 v[6:7], v[6:7], v[140:141]
	v_pk_add_f32 v[8:9], v[8:9], v[140:141]
	v_rcp_f32_e32 v14, v14
	v_rcp_f32_e32 v15, v15
	v_rcp_f32_e32 v16, v16
	v_rcp_f32_e32 v17, v17
	v_rcp_f32_e32 v6, v6
	v_rcp_f32_e32 v7, v7
	v_rcp_f32_e32 v8, v8
	v_rcp_f32_e32 v9, v9
	s_nop 0
	v_pk_mul_f32 v[10:11], v[10:11], v[14:15]
	v_pk_mul_f32 v[12:13], v[12:13], v[16:17]
	v_pk_mul_f32 v[2:3], v[2:3], v[6:7]
	v_pk_mul_f32 v[4:5], v[4:5], v[8:9]
	v_cvt_pk_bf16_f32 v14, v10, v11
	v_cvt_pk_bf16_f32 v15, v12, v13
	v_cvt_pk_bf16_f32 v16, v2, v3
	v_cvt_pk_bf16_f32 v17, v4, v5
	global_store_dwordx4 v[156:157], v[14:17], off
	s_mov_b64 s[6:7], -1
	s_andn2_b64 vcc, exec, s[0:1]
	s_cbranch_vccnz .LBB0_90
	s_andn2_b64 vcc, exec, s[4:5]
	s_cbranch_vccnz .LBB0_89
	s_barrier
	s_branch .LBB0_89

; #define LAS __attribute__((address_space(3)))
; __device__ __forceinline__ unsigned pk2(float lo, float hi) { unsigned r; asm("v_cvt_pk_bf16_f32 %0, %1, %2" : "=v"(r) : "v"(lo), "v"(hi)); return r; }
; __device__ __forceinline__ void hgrn_chain(const Params& p, LAS unsigned char* lds, int layer, int chain, int dvh) {
;     ...
;             const LAS float* GT = (const LAS float*)(lds + H_GT + cur * 2048);
;             const f32x4 g0 = *(const LAS f32x4*)(GT + wave * 16 + fq * 4), g1 = *(const LAS f32x4*)(GT + 128 + wave * 16 + fq * 4);
;             const f32x4 g2 = *(const LAS f32x4*)(GT + 256 + wave * 16 + fq * 4), g3 = *(const LAS f32x4*)(GT + 384 + wave * 16 + fq * 4);
;             eb = g0 * g1; ec = g2 * g3;
;         }
; #pragma unroll
;         for (int dvt = 0; dvt < 4; ++dvt) {
;             Sacc[dvt] = Sacc[dvt] * eb;
;             u32x2 w; w.x = pk2(Sacc[dvt][0], Sacc[dvt][1]); w.y = pk2(Sacc[dvt][2], Sacc[dvt][3]);
;             *(LAS u32x2*)(lds + H_ST + (dvt * 16 + fr) * H_QS + (wave * 16 + fq * 4) * 2) = w;
;         }
;         {
;             const int tt = wave >> 1;
; #pragma unroll
;             for (int u = 0; u < 2; ++u) {
;                 const int st = (wave & 1) * 2 + u;
;                 f32x4 a4 = (f32x4){0.f, 0.f, 0.f, 0.f};
;                 if (st <= tt) {
; #pragma unroll
;                     for (int kk = 0; kk < 4; ++kk) {
;                         const bf16x8 ka = *(const LAS bf16x8*)(lc + HB_KI + (st * 16 + fr) * H_QS + (kk * 32 + fq * 8) * 2);
;                         const bf16x8 qb = *(const LAS bf16x8*)(lc + HB_QI + (tt * 16 + fr) * H_QS + (kk * 32 + fq * 8) * 2);
;                         a4 = __builtin_amdgcn_mfma_f32_16x16x32_bf16(ka, qb, a4, 0, 0, 0);
;                     }
;                     const int t = tt * 16 + fr;
; #pragma unroll
;                     for (int j = 0; j < 4; ++j) { const int s = st * 16 + fq * 4 + j; a4[j] = (s <= t) ? a4[j] : 0.f; }
;                 }
;                 u32x2 w; w.x = pk2(a4[0], a4[1]); w.y = pk2(a4[2], a4[3]);
;                 *(LAS u32x2*)(lds + H_PM + (tt * 16 + fr) * H_TS + (st * 16 + fq * 4) * 2) = w;
.LBB0_422:
	s_and_b32 s0, s56, 1
	v_lshl_add_u32 v14, s0, 11, v136
	ds_read_b128 v[34:37], v14
	ds_read_b128 v[154:157], v14 offset:512
	ds_read_b128 v[10:13], v14 offset:1024
	ds_read_b128 v[14:17], v14 offset:1536
	s_mul_i32 s1, s0, 0xf400
	s_add_i32 s58, s1, 0
	s_andn2_b64 vcc, exec, s[74:75]
	s_waitcnt lgkmcnt(2)
	v_pk_mul_f32 v[34:35], v[34:35], v[154:155]
	v_pk_mul_f32 v[36:37], v[36:37], v[156:157]
	v_pk_mul_f32 v[18:19], v[18:19], v[34:35]
	v_pk_mul_f32 v[22:23], v[22:23], v[34:35]
	v_pk_mul_f32 v[26:27], v[26:27], v[34:35]
	v_pk_mul_f32 v[30:31], v[30:31], v[34:35]
	v_pk_mul_f32 v[20:21], v[20:21], v[36:37]
	v_cvt_pk_bf16_f32 v34, v30, v31
	v_cvt_pk_bf16_f32 v154, v18, v19
	v_pk_mul_f32 v[32:33], v[32:33], v[36:37]
	v_cvt_pk_bf16_f32 v155, v20, v21
	ds_write_b64 v141, v[154:155]
	v_cvt_pk_bf16_f32 v35, v32, v33
	ds_write_b64 v141, v[34:35] offset:13056
	v_add_u32_e32 v34, s58, v125
	v_pk_mul_f32 v[24:25], v[24:25], v[36:37]
	v_cvt_pk_bf16_f32 v154, v22, v23
	v_pk_mul_f32 v[28:29], v[28:29], v[36:37]
	v_cvt_pk_bf16_f32 v155, v24, v25
	v_add_u32_e32 v34, v34, v124
	v_mov_b32_e32 v35, 0
	v_mov_b32_e32 v36, 0
	v_mov_b32_e32 v37, 0
	v_mov_b32_e32 v85, 0
	ds_write_b64 v141, v[154:155] offset:4352
	v_cvt_pk_bf16_f32 v154, v26, v27
	v_cvt_pk_bf16_f32 v155, v28, v29
	ds_write_b64 v141, v[154:155] offset:8704
	s_cbranch_vccnz .LBB0_424
	v_add3_u32 v35, s58, v129, v124
	ds_read_b128 v[154:157], v35 offset:17408
	ds_read_b128 v[158:161], v34
	ds_read_b128 v[162:165], v35 offset:17472
	ds_read_b128 v[166:169], v34 offset:64
	ds_read_b128 v[170:173], v35 offset:17536
	ds_read_b128 v[174:177], v34 offset:128
	s_waitcnt lgkmcnt(4)
	v_mfma_f32_16x16x32_bf16 v[154:157], v[154:157], v[158:161], 0
	ds_read_b128 v[158:161], v35 offset:17600
	s_waitcnt lgkmcnt(3)
	v_mfma_f32_16x16x32_bf16 v[154:157], v[162:165], v[166:169], v[154:157]
	ds_read_b128 v[166:169], v34 offset:192
	s_waitcnt lgkmcnt(2)
	v_mfma_f32_16x16x32_bf16 v[154:157], v[170:173], v[174:177], v[154:157]
	s_waitcnt lgkmcnt(0)
	v_mfma_f32_16x16x32_bf16 v[154:157], v[158:161], v[166:169], v[154:157]
	s_nop 7
	v_cndmask_b32_e64 v35, v154, 0, s[18:19]
	v_cndmask_b32_e64 v36, 0, v155, s[20:21]
	v_cndmask_b32_e64 v37, v156, 0, s[22:23]
	v_cndmask_b32_e64 v85, v157, 0, s[24:25]
.LBB0_424:
	v_cvt_pk_bf16_f32 v36, v35, v36
	v_cvt_pk_bf16_f32 v37, v37, v85
	v_add_u32_e32 v35, s73, v126
	ds_write_b64 v35, v[36:37]
	v_mov_b32_e32 v35, 0
	s_andn2_b64 vcc, exec, s[76:77]
	v_mov_b32_e32 v36, 0
	v_mov_b32_e32 v37, 0
	v_mov_b32_e32 v85, 0
	s_cbranch_vccnz .LBB0_426
	v_add3_u32 v35, s58, v130, v124
	ds_read_b128 v[154:157], v35 offset:17408
	ds_read_b128 v[158:161], v34
	ds_read_b128 v[162:165], v35 offset:17472
	ds_read_b128 v[166:169], v34 offset:64
	ds_read_b128 v[170:173], v35 offset:17536
	ds_read_b128 v[174:177], v34 offset:128
	s_waitcnt lgkmcnt(4)
	v_mfma_f32_16x16x32_bf16 v[154:157], v[154:157], v[158:161], 0
	ds_read_b128 v[158:161], v35 offset:17600
	s_waitcnt lgkmcnt(3)
	v_mfma_f32_16x16x32_bf16 v[154:157], v[162:165], v[166:169], v[154:157]
	ds_read_b128 v[166:169], v34 offset:192
	s_waitcnt lgkmcnt(2)
	v_mfma_f32_16x16x32_bf16 v[154:157], v[170:173], v[174:177], v[154:157]
	s_waitcnt lgkmcnt(0)
	v_mfma_f32_16x16x32_bf16 v[154:157], v[158:161], v[166:169], v[154:157]
	s_nop 7
	v_cndmask_b32_e64 v35, v154, 0, s[26:27]
	v_cndmask_b32_e64 v36, 0, v155, s[28:29]
	v_cndmask_b32_e64 v37, v156, 0, s[30:31]
	v_cndmask_b32_e64 v85, v157, 0, s[34:35]

; #define LAS __attribute__((address_space(3)))
; __device__ __forceinline__ void hgrn_chain(const Params& p, LAS unsigned char* lds, int layer, int chain, int dvh) {
;     ...
;         {
;             const int dvt = wave & 3;
;             bf16x8 va[2], sa[4];
; #pragma unroll
;             for (int ks = 0; ks < 2; ++ks) va[ks] = *(const LAS bf16x8*)(lc + HB_VT + (dvt * 16 + fr) * H_TS + (ks * 32 + fq * 8) * 2);
; #pragma unroll
;             for (int kk = 0; kk < 4; ++kk) sa[kk] = *(const LAS bf16x8*)(lds + H_ST + (dvt * 16 + fr) * H_QS + (kk * 32 + fq * 8) * 2);
; #pragma unroll
;             for (int u = 0; u < 2; ++u) {
;                 const int tt = (wave >> 2) * 2 + u;
;                 f32x4 o4 = (f32x4){0.f, 0.f, 0.f, 0.f};
; #pragma unroll
;                 for (int ks = 0; ks < 2; ++ks) { const bf16x8 pbf = *(const LAS bf16x8*)(lds + H_PM + (tt * 16 + fr) * H_TS + (ks * 32 + fq * 8) * 2); o4 = __builtin_amdgcn_mfma_f32_16x16x32_bf16(va[ks], pbf, o4, 0, 0, 0); }
; #pragma unroll
;                 for (int kk = 0; kk < 4; ++kk) { const bf16x8 qb = *(const LAS bf16x8*)(lc + HB_QI + (tt * 16 + fr) * H_QS + (kk * 32 + fq * 8) * 2); o4 = __builtin_amdgcn_mfma_f32_16x16x32_bf16(sa[kk], qb, o4, 0, 0, 0); }
;                 *(f32x4*)(O + HG_TOK(c, tt * 16 + fr) * RGW + h * 128 + dvh * 64 + dvt * 16 + fq * 4) = o4;
;             }
;         }
;         {
;             bf16x8 ka[2];
; #pragma unroll
;             for (int ks = 0; ks < 2; ++ks) ka[ks] = *(const LAS bf16x8*)(lc + HB_KIT + (wave * 16 + fr) * H_TS + (ks * 32 + fq * 8) * 2);
; #pragma unroll
;             for (int dvt = 0; dvt < 4; ++dvt) {
; #pragma unroll
;                 for (int ks = 0; ks < 2; ++ks) { const bf16x8 vb = *(const LAS bf16x8*)(lc + HB_VT + (dvt * 16 + fr) * H_TS + (ks * 32 + fq * 8) * 2); Sacc[dvt] = __builtin_amdgcn_mfma_f32_16x16x32_bf16(ka[ks], vb, Sacc[dvt], 0, 0, 0); }
;                 Sacc[dvt] = Sacc[dvt] * ec;
;             }
.LBB0_442:
	v_add_u32_e32 v85, s58, v124
	s_waitcnt lgkmcnt(0)
	s_barrier
	v_add_u32_e32 v153, v85, v127
	v_add_u32_e32 v178, v85, v132
	v_add_u32_e32 v179, v85, v134
	ds_read_b128 v[158:161], v153 offset:53248
	ds_read_b128 v[162:165], v143
	ds_read_b128 v[166:169], v144
	ds_read_b128 v[170:173], v153 offset:53312
	ds_read_b128 v[174:177], v143 offset:64
	ds_read_b128 v[234:237], v144 offset:64
	ds_read_b128 v[238:241], v142
	ds_read_b128 v[242:245], v178
	ds_read_b128 v[246:249], v179
	s_andn2_b64 vcc, exec, s[70:71]
	v_add_u32_e32 v214, v85, v128
	v_add_u32_e32 v215, v85, v135
	s_waitcnt lgkmcnt(7)
	v_mfma_f32_16x16x32_bf16 v[154:157], v[158:161], v[162:165], 0
	s_waitcnt lgkmcnt(6)
	v_mfma_f32_16x16x32_bf16 v[34:37], v[158:161], v[166:169], 0
	ds_read_b128 v[158:161], v142 offset:64
	ds_read_b128 v[162:165], v178 offset:64
	ds_read_b128 v[166:169], v179 offset:64
	s_waitcnt lgkmcnt(7)
	v_mfma_f32_16x16x32_bf16 v[154:157], v[170:173], v[174:177], v[154:157]
	s_waitcnt lgkmcnt(6)
	v_mfma_f32_16x16x32_bf16 v[34:37], v[170:173], v[234:237], v[34:37]
	ds_read_b128 v[170:173], v142 offset:128
	ds_read_b128 v[174:177], v178 offset:128
	ds_read_b128 v[234:237], v179 offset:128
	s_waitcnt lgkmcnt(7)
	v_mfma_f32_16x16x32_bf16 v[154:157], v[238:241], v[242:245], v[154:157]
	s_waitcnt lgkmcnt(6)
	v_mfma_f32_16x16x32_bf16 v[34:37], v[238:241], v[246:249], v[34:37]
	ds_read_b128 v[238:241], v142 offset:192
	ds_read_b128 v[242:245], v178 offset:192
	ds_read_b128 v[246:249], v179 offset:192
	s_waitcnt lgkmcnt(7)
	v_mfma_f32_16x16x32_bf16 v[154:157], v[158:161], v[162:165], v[154:157]
	s_waitcnt lgkmcnt(6)
	v_mfma_f32_16x16x32_bf16 v[34:37], v[158:161], v[166:169], v[34:37]
	ds_read_b128 v[158:161], v214 offset:34816
	ds_read_b128 v[162:165], v215 offset:53248
	ds_read_b128 v[166:169], v214 offset:34880
	s_waitcnt lgkmcnt(7)
	v_mfma_f32_16x16x32_bf16 v[154:157], v[170:173], v[174:177], v[154:157]
	s_waitcnt lgkmcnt(6)
	v_mfma_f32_16x16x32_bf16 v[34:37], v[170:173], v[234:237], v[34:37]
	ds_read_b128 v[170:173], v215 offset:53312
	ds_read_b128 v[174:177], v215 offset:55552
	ds_read_b128 v[234:237], v215 offset:55616
	s_waitcnt lgkmcnt(7)
	v_mfma_f32_16x16x32_bf16 v[154:157], v[238:241], v[242:245], v[154:157]
	s_waitcnt lgkmcnt(6)
	v_mfma_f32_16x16x32_bf16 v[34:37], v[238:241], v[246:249], v[34:37]
	ds_read_b128 v[238:241], v215 offset:57856
	ds_read_b128 v[242:245], v215 offset:57920
	ds_read_b128 v[246:249], v215 offset:60160
	v_add_u32_e32 v153, s72, v140
	v_cndmask_b32_e64 v224, v153, v131, s[10:11]
	v_ashrrev_i32_e32 v225, 31, v224
	v_lshl_add_u64 v[224:225], s[4:5], 0, v[224:225]
	v_lshlrev_b64 v[224:225], 12, v[224:225]
	v_lshl_add_u64 v[224:225], v[52:53], 0, v[224:225]
	s_waitcnt lgkmcnt(7)
	v_mfma_f32_16x16x32_bf16 v[18:21], v[158:161], v[162:165], v[18:21]
	ds_read_b128 v[162:165], v215 offset:60224
	v_add_u32_e32 v153, s72, v139
	v_cndmask_b32_e64 v250, v153, v133, s[10:11]
	v_ashrrev_i32_e32 v251, 31, v250
	s_waitcnt lgkmcnt(6)
	v_mfma_f32_16x16x32_bf16 v[18:21], v[166:169], v[170:173], v[18:21]
	v_lshl_add_u64 v[250:251], s[4:5], 0, v[250:251]
	v_lshlrev_b64 v[250:251], 12, v[250:251]
	s_waitcnt lgkmcnt(5)
	v_mfma_f32_16x16x32_bf16 v[22:25], v[158:161], v[174:177], v[22:25]
	global_store_dwordx4 v[224:225], v[154:157], off
	v_lshl_add_u64 v[250:251], v[52:53], 0, v[250:251]
	s_waitcnt lgkmcnt(4)
	v_mfma_f32_16x16x32_bf16 v[22:25], v[166:169], v[234:237], v[22:25]
	s_waitcnt lgkmcnt(3)
	v_mfma_f32_16x16x32_bf16 v[26:29], v[158:161], v[238:241], v[26:29]
	global_store_dwordx4 v[250:251], v[34:37], off
	s_waitcnt lgkmcnt(2)
	v_mfma_f32_16x16x32_bf16 v[26:29], v[166:169], v[242:245], v[26:29]
	s_waitcnt lgkmcnt(1)
	v_mfma_f32_16x16x32_bf16 v[30:33], v[158:161], v[246:249], v[30:33]
	s_waitcnt lgkmcnt(0)
	v_mfma_f32_16x16x32_bf16 v[30:33], v[166:169], v[162:165], v[30:33]
	s_cbranch_vccnz .LBB0_421
	s_lshl_b32 s0, s57, 11
	s_add_i32 s0, s0, 0
	s_add_i32 s0, s0, 0x25000
	v_lshl_add_u32 v35, v86, 2, s0
	s_and_saveexec_b64 s[0:1], s[14:15]
	s_xor_b64 s[0:1], exec, s[0:1]
	s_cbranch_execz .LBB0_445
	ds_read2st64_b32 v[34:35], v35 offset1:2
	s_waitcnt lgkmcnt(0)
	v_mul_f32_e32 v34, v34, v35
	v_cndmask_b32_e64 v34, v35, v34, s[12:13]
	v_max_f32_e32 v34, v34, v34
	v_max_f32_e32 v34, 0x3aa2425, v34
	v_rcp_f32_e32 v34, v34

; __device__ __forceinline__ unsigned pk2(float lo, float hi) { unsigned r; asm("v_cvt_pk_bf16_f32 %0, %1, %2" : "=v"(r) : "v"(lo), "v"(hi)); return r; }
; __device__ __forceinline__ float sigmoidf_(float v) { return __builtin_amdgcn_rcpf(1.0f + fexp(-v)); }
; __device__ __forceinline__ void row_rstd8(const ssq_t* ss, int row0, float (&r)[8]) {
;     ssq_t sv[8];
; #pragma unroll
;     for (int k = 0; k < 8; ++k) sv[k] = ss[row0 + (k >> 2) * 128 + (k & 3) * 16];
;     asm volatile("" ::: "memory");
; #pragma unroll
;     for (int k = 0; k < 8; ++k) r[k] = rsqrtf((float)sv[k] * (1.0f / SSQ_SCALE) * (1.0f / D) + EPS);
; }
; __device__ __forceinline__ float row_rstd(const ssq_t* ss, int row) { return rsqrtf((float)ss[row] * (1.0f / SSQ_SCALE) * (1.0f / D) + EPS); }
;     __device__ __forceinline__ bool operator()(f32x4 (&acc)[2][2][4][2], const pg8::Unit& u, int wr, int wc, int fr, int fq) const {
;         const int row0 = u.pm * 256 + wr * 64 + fr, col0 = u.pn * 128 + wc * 32 + 8 * fq;
;         float rr[8]; row_rstd8(ss, row0, rr);
; #pragma unroll
;         for (int ai = 0; ai < 2; ++ai)
; #pragma unroll
;             for (int m = 0; m < 4; ++m) {
;                 const int row = row0 + ai * 128 + m * 16; const float r = rr[ai * 4 + m];
;                 float o[8];
; #pragma unroll
;                 for (int n = 0; n < 2; ++n)
; #pragma unroll
;                     for (int j = 0; j < 4; ++j) { const float gv = acc[ai][0][m][n][j] * r, uv = acc[ai][1][m][n][j] * r; o[n * 4 + j] = gv * sigmoidf_(gv) * uv; }
;                 u32x4 w; w.x = pk2(o[0], o[1]); w.y = pk2(o[2], o[3]); w.z = pk2(o[4], o[5]); w.w = pk2(o[6], o[7]);
;                 *(u32x4*)(act + (size_t)row * FF + col0) = w;
.LBB0_874:
	v_lshl_add_u32 v140, s57, 8, v151
	v_ashrrev_i32_e32 v141, 31, v140
	v_lshl_or_b32 v156, s56, 7, v155
	v_ashrrev_i32_e32 v157, 31, v156
	v_lshl_add_u64 v[142:143], v[140:141], 3, s[0:1]
	global_load_dwordx2 v[160:161], v[142:143], off
	global_load_dwordx2 v[162:163], v[142:143], off offset:128
	global_load_dwordx2 v[164:165], v[142:143], off offset:256
	global_load_dwordx2 v[166:167], v[142:143], off offset:384
	global_load_dwordx2 v[146:147], v[142:143], off offset:1024
	global_load_dwordx2 v[148:149], v[142:143], off offset:1152
	global_load_dwordx2 v[144:145], v[142:143], off offset:1280
	s_nop 0
	global_load_dwordx2 v[142:143], v[142:143], off offset:1408
	v_lshlrev_b64 v[156:157], 1, v[156:157]
	v_lshl_add_u64 v[156:157], v[156:157], 0, s[90:91]
	v_mad_i64_i32 v[156:157], s[4:5], v140, s37, v[156:157]
	v_mov_b32_e32 v140, 1.0
	v_mov_b32_e32 v141, 1.0
	v_pk_mul_f32 v[122:123], v[122:123], v[126:127]
	v_pk_mul_f32 v[124:125], v[124:125], v[128:129]
	v_pk_mul_f32 v[114:115], v[114:115], v[118:119]
	v_pk_mul_f32 v[116:117], v[116:117], v[120:121]
	v_pk_mul_f32 v[106:107], v[106:107], v[110:111]
	v_pk_mul_f32 v[108:109], v[108:109], v[112:113]
	v_pk_mul_f32 v[98:99], v[98:99], v[102:103]
	v_pk_mul_f32 v[100:101], v[100:101], v[104:105]
	v_pk_mul_f32 v[90:91], v[90:91], v[94:95]
	v_pk_mul_f32 v[92:93], v[92:93], v[96:97]
	v_pk_mul_f32 v[82:83], v[82:83], v[86:87]
	v_pk_mul_f32 v[84:85], v[84:85], v[88:89]
	v_pk_mul_f32 v[74:75], v[74:75], v[78:79]
	v_pk_mul_f32 v[76:77], v[76:77], v[80:81]
	v_pk_mul_f32 v[66:67], v[66:67], v[70:71]
	v_pk_mul_f32 v[68:69], v[68:69], v[72:73]
	v_pk_mul_f32 v[58:59], v[58:59], v[62:63]
	v_pk_mul_f32 v[60:61], v[60:61], v[64:65]
	v_pk_mul_f32 v[50:51], v[50:51], v[54:55]
	v_pk_mul_f32 v[52:53], v[52:53], v[56:57]
	v_pk_mul_f32 v[42:43], v[42:43], v[46:47]
	v_pk_mul_f32 v[44:45], v[44:45], v[48:49]
	v_pk_mul_f32 v[34:35], v[34:35], v[38:39]
	v_pk_mul_f32 v[36:37], v[36:37], v[40:41]
	v_pk_mul_f32 v[26:27], v[26:27], v[30:31]
	v_pk_mul_f32 v[28:29], v[28:29], v[32:33]
	v_pk_mul_f32 v[18:19], v[18:19], v[22:23]
	v_pk_mul_f32 v[20:21], v[20:21], v[24:25]
	v_pk_mul_f32 v[10:11], v[10:11], v[14:15]
	v_pk_mul_f32 v[12:13], v[12:13], v[16:17]
	v_pk_mul_f32 v[2:3], v[2:3], v[6:7]
	v_pk_mul_f32 v[4:5], v[4:5], v[8:9]
	s_mov_b32 s4, 0x2c000
	s_mov_b32 s5, 0
	s_waitcnt vmcnt(0)
	v_ffbh_u32_e32 v150, v161
	v_min_u32_e32 v150, 32, v150
	v_lshlrev_b64 v[160:161], v150, v[160:161]
	v_min_u32_e32 v152, 1, v160
	v_or_b32_e32 v152, v161, v152
	v_cvt_f32_u32_e32 v152, v152
	v_sub_u32_e32 v150, 32, v150
	v_ldexp_f32 v152, v152, v150
	v_mul_f32_e32 v152, 0x33800000, v152
	v_fmamk_f32 v152, v152, 0x3a000000, v218
	v_rsq_f32_e32 v160, v152
	v_ffbh_u32_e32 v150, v163
	v_min_u32_e32 v150, 32, v150
	v_lshlrev_b64 v[162:163], v150, v[162:163]
	v_min_u32_e32 v152, 1, v162
	v_or_b32_e32 v152, v163, v152
	v_cvt_f32_u32_e32 v152, v152
	v_sub_u32_e32 v150, 32, v150
	v_ldexp_f32 v152, v152, v150
	v_mul_f32_e32 v152, 0x33800000, v152
	v_fmamk_f32 v152, v152, 0x3a000000, v218
	v_rsq_f32_e32 v162, v152
	v_ffbh_u32_e32 v150, v165
	v_min_u32_e32 v150, 32, v150
	v_lshlrev_b64 v[164:165], v150, v[164:165]
	v_min_u32_e32 v152, 1, v164
	v_or_b32_e32 v152, v165, v152
	v_cvt_f32_u32_e32 v152, v152
	v_sub_u32_e32 v150, 32, v150
	v_ldexp_f32 v152, v152, v150
	v_mul_f32_e32 v152, 0x33800000, v152
	v_fmamk_f32 v152, v152, 0x3a000000, v218
	v_rsq_f32_e32 v164, v152
	v_ffbh_u32_e32 v150, v167
	v_min_u32_e32 v150, 32, v150
	v_lshlrev_b64 v[166:167], v150, v[166:167]
	v_min_u32_e32 v152, 1, v166
	v_or_b32_e32 v152, v167, v152
	v_cvt_f32_u32_e32 v152, v152
	v_sub_u32_e32 v150, 32, v150
	v_ldexp_f32 v152, v152, v150
	v_mul_f32_e32 v152, 0x33800000, v152
	v_fmamk_f32 v152, v152, 0x3a000000, v218
	v_rsq_f32_e32 v166, v152
	v_ffbh_u32_e32 v150, v147
	v_min_u32_e32 v150, 32, v150
	v_lshlrev_b64 v[146:147], v150, v[146:147]
	v_min_u32_e32 v152, 1, v146
	v_or_b32_e32 v152, v147, v152
	v_cvt_f32_u32_e32 v152, v152
	v_sub_u32_e32 v150, 32, v150
	v_ldexp_f32 v152, v152, v150
	v_mul_f32_e32 v152, 0x33800000, v152
	v_fmamk_f32 v152, v152, 0x3a000000, v218
	v_rsq_f32_e32 v146, v152
	v_ffbh_u32_e32 v150, v149
	v_min_u32_e32 v150, 32, v150
	v_lshlrev_b64 v[148:149], v150, v[148:149]
	v_min_u32_e32 v152, 1, v148
	v_or_b32_e32 v152, v149, v152
	v_cvt_f32_u32_e32 v152, v152
	v_sub_u32_e32 v150, 32, v150
	v_ldexp_f32 v152, v152, v150
	v_mul_f32_e32 v152, 0x33800000, v152
	v_fmamk_f32 v152, v152, 0x3a000000, v218
	v_rsq_f32_e32 v148, v152
	v_ffbh_u32_e32 v150, v145
	v_min_u32_e32 v150, 32, v150
	v_lshlrev_b64 v[144:145], v150, v[144:145]
	v_min_u32_e32 v152, 1, v144
	v_or_b32_e32 v152, v145, v152
	v_cvt_f32_u32_e32 v152, v152
	v_sub_u32_e32 v150, 32, v150
	v_ldexp_f32 v152, v152, v150
	v_mul_f32_e32 v152, 0x33800000, v152
	v_fmamk_f32 v152, v152, 0x3a000000, v218
	v_rsq_f32_e32 v144, v152
	v_ffbh_u32_e32 v150, v143
	v_min_u32_e32 v150, 32, v150
	v_lshlrev_b64 v[142:143], v150, v[142:143]
	v_min_u32_e32 v152, 1, v142
	v_or_b32_e32 v152, v143, v152
	v_cvt_f32_u32_e32 v152, v152
	v_sub_u32_e32 v150, 32, v150
	v_ldexp_f32 v152, v152, v150
	v_mul_f32_e32 v152, 0x33800000, v152
	v_fmamk_f32 v152, v152, 0x3a000000, v218
	v_rsq_f32_e32 v142, v152
	s_nop 0
	v_mul_f32_e32 v150, 0xbfb8aa3b, v160
	v_mul_f32_e32 v152, v160, v160
	v_pk_mul_f32 v[126:127], v[126:127], v[150:151] op_sel_hi:[1,0]
	v_pk_mul_f32 v[128:129], v[128:129], v[150:151] op_sel_hi:[1,0]
	v_pk_mul_f32 v[118:119], v[118:119], v[150:151] op_sel_hi:[1,0]
	v_pk_mul_f32 v[120:121], v[120:121], v[150:151] op_sel_hi:[1,0]
	v_exp_f32_e32 v126, v126
	v_exp_f32_e32 v127, v127
	v_exp_f32_e32 v128, v128
	v_exp_f32_e32 v129, v129
; __device__ __forceinline__ unsigned pk2(float lo, float hi) { unsigned r; asm("v_cvt_pk_bf16_f32 %0, %1, %2" : "=v"(r) : "v"(lo), "v"(hi)); return r; }
; __device__ __forceinline__ float sigmoidf_(float v) { return __builtin_amdgcn_rcpf(1.0f + fexp(-v)); }
;     __device__ __forceinline__ bool operator()(f32x4 (&acc)[2][2][4][2], const pg8::Unit& u, int wr, int wc, int fr, int fq) const {
;     ...
;                 const int row = row0 + ai * 128 + m * 16; const float r = rr[ai * 4 + m];
;                 float o[8];
; #pragma unroll
;                 for (int n = 0; n < 2; ++n)
; #pragma unroll
;                     for (int j = 0; j < 4; ++j) { const float gv = acc[ai][0][m][n][j] * r, uv = acc[ai][1][m][n][j] * r; o[n * 4 + j] = gv * sigmoidf_(gv) * uv; }
;                 u32x4 w; w.x = pk2(o[0], o[1]); w.y = pk2(o[2], o[3]); w.z = pk2(o[4], o[5]); w.w = pk2(o[6], o[7]);
;                 *(u32x4*)(act + (size_t)row * FF + col0) = w;
	v_exp_f32_e32 v118, v118
	v_exp_f32_e32 v119, v119
	v_exp_f32_e32 v120, v120
	v_exp_f32_e32 v121, v121
	v_pk_mul_f32 v[122:123], v[122:123], v[152:153] op_sel_hi:[1,0]
	v_pk_mul_f32 v[124:125], v[124:125], v[152:153] op_sel_hi:[1,0]
	v_pk_mul_f32 v[114:115], v[114:115], v[152:153] op_sel_hi:[1,0]
	v_pk_mul_f32 v[116:117], v[116:117], v[152:153] op_sel_hi:[1,0]
	v_pk_add_f32 v[126:127], v[126:127], v[140:141]
	v_pk_add_f32 v[128:129], v[128:129], v[140:141]
	v_pk_add_f32 v[118:119], v[118:119], v[140:141]
	v_pk_add_f32 v[120:121], v[120:121], v[140:141]
	v_rcp_f32_e32 v126, v126
	v_rcp_f32_e32 v127, v127
	v_rcp_f32_e32 v128, v128
	v_rcp_f32_e32 v129, v129
	v_rcp_f32_e32 v118, v118
	v_rcp_f32_e32 v119, v119
	v_rcp_f32_e32 v120, v120
	v_rcp_f32_e32 v121, v121
	s_nop 0
	v_pk_mul_f32 v[122:123], v[122:123], v[126:127]
	v_pk_mul_f32 v[124:125], v[124:125], v[128:129]
	v_pk_mul_f32 v[114:115], v[114:115], v[118:119]
	v_pk_mul_f32 v[116:117], v[116:117], v[120:121]
	v_cvt_pk_bf16_f32 v126, v122, v123
	v_cvt_pk_bf16_f32 v127, v124, v125
	v_cvt_pk_bf16_f32 v128, v114, v115
	v_cvt_pk_bf16_f32 v129, v116, v117
	global_store_dwordx4 v[156:157], v[126:129], off
	v_lshl_add_u64 v[156:157], v[156:157], 0, s[4:5]
	v_mul_f32_e32 v150, 0xbfb8aa3b, v162
	v_mul_f32_e32 v152, v162, v162
	v_pk_mul_f32 v[110:111], v[110:111], v[150:151] op_sel_hi:[1,0]
	v_pk_mul_f32 v[112:113], v[112:113], v[150:151] op_sel_hi:[1,0]
	v_pk_mul_f32 v[102:103], v[102:103], v[150:151] op_sel_hi:[1,0]
	v_pk_mul_f32 v[104:105], v[104:105], v[150:151] op_sel_hi:[1,0]
	v_exp_f32_e32 v110, v110
	v_exp_f32_e32 v111, v111
	v_exp_f32_e32 v112, v112
	v_exp_f32_e32 v113, v113
	v_exp_f32_e32 v102, v102
	v_exp_f32_e32 v103, v103
	v_exp_f32_e32 v104, v104
	v_exp_f32_e32 v105, v105
	v_pk_mul_f32 v[106:107], v[106:107], v[152:153] op_sel_hi:[1,0]
	v_pk_mul_f32 v[108:109], v[108:109], v[152:153] op_sel_hi:[1,0]
	v_pk_mul_f32 v[98:99], v[98:99], v[152:153] op_sel_hi:[1,0]
	v_pk_mul_f32 v[100:101], v[100:101], v[152:153] op_sel_hi:[1,0]
	v_pk_add_f32 v[110:111], v[110:111], v[140:141]
	v_pk_add_f32 v[112:113], v[112:113], v[140:141]
	v_pk_add_f32 v[102:103], v[102:103], v[140:141]
	v_pk_add_f32 v[104:105], v[104:105], v[140:141]
	v_rcp_f32_e32 v110, v110
	v_rcp_f32_e32 v111, v111
	v_rcp_f32_e32 v112, v112
	v_rcp_f32_e32 v113, v113
	v_rcp_f32_e32 v102, v102
	v_rcp_f32_e32 v103, v103
	v_rcp_f32_e32 v104, v104
	v_rcp_f32_e32 v105, v105
	s_nop 0
	v_pk_mul_f32 v[106:107], v[106:107], v[110:111]
	v_pk_mul_f32 v[108:109], v[108:109], v[112:113]
	v_pk_mul_f32 v[98:99], v[98:99], v[102:103]
	v_pk_mul_f32 v[100:101], v[100:101], v[104:105]
	v_cvt_pk_bf16_f32 v110, v106, v107
	v_cvt_pk_bf16_f32 v111, v108, v109
	v_cvt_pk_bf16_f32 v112, v98, v99
	v_cvt_pk_bf16_f32 v113, v100, v101
	global_store_dwordx4 v[156:157], v[110:113], off
	v_lshl_add_u64 v[156:157], v[156:157], 0, s[4:5]
	v_mul_f32_e32 v150, 0xbfb8aa3b, v164
	v_mul_f32_e32 v152, v164, v164
	v_pk_mul_f32 v[94:95], v[94:95], v[150:151] op_sel_hi:[1,0]
	v_pk_mul_f32 v[96:97], v[96:97], v[150:151] op_sel_hi:[1,0]
	v_pk_mul_f32 v[86:87], v[86:87], v[150:151] op_sel_hi:[1,0]
	v_pk_mul_f32 v[88:89], v[88:89], v[150:151] op_sel_hi:[1,0]
	v_exp_f32_e32 v94, v94
	v_exp_f32_e32 v95, v95
	v_exp_f32_e32 v96, v96
	v_exp_f32_e32 v97, v97
	v_exp_f32_e32 v86, v86
	v_exp_f32_e32 v87, v87
	v_exp_f32_e32 v88, v88
	v_exp_f32_e32 v89, v89
	v_pk_mul_f32 v[90:91], v[90:91], v[152:153] op_sel_hi:[1,0]
	v_pk_mul_f32 v[92:93], v[92:93], v[152:153] op_sel_hi:[1,0]
	v_pk_mul_f32 v[82:83], v[82:83], v[152:153] op_sel_hi:[1,0]
	v_pk_mul_f32 v[84:85], v[84:85], v[152:153] op_sel_hi:[1,0]
	v_pk_add_f32 v[94:95], v[94:95], v[140:141]
	v_pk_add_f32 v[96:97], v[96:97], v[140:141]
	v_pk_add_f32 v[86:87], v[86:87], v[140:141]
	v_pk_add_f32 v[88:89], v[88:89], v[140:141]
	v_rcp_f32_e32 v94, v94
	v_rcp_f32_e32 v95, v95
	v_rcp_f32_e32 v96, v96
	v_rcp_f32_e32 v97, v97
	v_rcp_f32_e32 v86, v86
	v_rcp_f32_e32 v87, v87
	v_rcp_f32_e32 v88, v88
	v_rcp_f32_e32 v89, v89
	s_nop 0
	v_pk_mul_f32 v[90:91], v[90:91], v[94:95]
	v_pk_mul_f32 v[92:93], v[92:93], v[96:97]
	v_pk_mul_f32 v[82:83], v[82:83], v[86:87]
	v_pk_mul_f32 v[84:85], v[84:85], v[88:89]
	v_cvt_pk_bf16_f32 v94, v90, v91
	v_cvt_pk_bf16_f32 v95, v92, v93
	v_cvt_pk_bf16_f32 v96, v82, v83
	v_cvt_pk_bf16_f32 v97, v84, v85
	global_store_dwordx4 v[156:157], v[94:97], off
	v_lshl_add_u64 v[156:157], v[156:157], 0, s[4:5]
	v_mul_f32_e32 v150, 0xbfb8aa3b, v166
	v_mul_f32_e32 v152, v166, v166
	v_pk_mul_f32 v[78:79], v[78:79], v[150:151] op_sel_hi:[1,0]
	v_pk_mul_f32 v[80:81], v[80:81], v[150:151] op_sel_hi:[1,0]
	v_pk_mul_f32 v[70:71], v[70:71], v[150:151] op_sel_hi:[1,0]
	v_pk_mul_f32 v[72:73], v[72:73], v[150:151] op_sel_hi:[1,0]
	v_exp_f32_e32 v78, v78
	v_exp_f32_e32 v79, v79
	v_exp_f32_e32 v80, v80
	v_exp_f32_e32 v81, v81
	v_exp_f32_e32 v70, v70
	v_exp_f32_e32 v71, v71
	v_exp_f32_e32 v72, v72
	v_exp_f32_e32 v73, v73
	v_pk_mul_f32 v[74:75], v[74:75], v[152:153] op_sel_hi:[1,0]
	v_pk_mul_f32 v[76:77], v[76:77], v[152:153] op_sel_hi:[1,0]
	v_pk_mul_f32 v[66:67], v[66:67], v[152:153] op_sel_hi:[1,0]
	v_pk_mul_f32 v[68:69], v[68:69], v[152:153] op_sel_hi:[1,0]
	v_pk_add_f32 v[78:79], v[78:79], v[140:141]
	v_pk_add_f32 v[80:81], v[80:81], v[140:141]
	v_pk_add_f32 v[70:71], v[70:71], v[140:141]
	v_pk_add_f32 v[72:73], v[72:73], v[140:141]
	v_rcp_f32_e32 v78, v78
	v_rcp_f32_e32 v79, v79
	v_rcp_f32_e32 v80, v80
	v_rcp_f32_e32 v81, v81
	v_rcp_f32_e32 v70, v70
	v_rcp_f32_e32 v71, v71
	v_rcp_f32_e32 v72, v72
	v_rcp_f32_e32 v73, v73
	s_nop 0
	v_pk_mul_f32 v[74:75], v[74:75], v[78:79]
	v_pk_mul_f32 v[76:77], v[76:77], v[80:81]
	v_pk_mul_f32 v[66:67], v[66:67], v[70:71]
; __device__ __forceinline__ unsigned pk2(float lo, float hi) { unsigned r; asm("v_cvt_pk_bf16_f32 %0, %1, %2" : "=v"(r) : "v"(lo), "v"(hi)); return r; }
; __device__ __forceinline__ float sigmoidf_(float v) { return __builtin_amdgcn_rcpf(1.0f + fexp(-v)); }
; #define PG8_BAR __builtin_amdgcn_s_barrier()
; template <class Epi, class Sched, bool ALIGN_EPI = true, bool SP2 = true>
; __device__ __forceinline__ void gemm_phase(LAS unsigned char* lds, const Gemm g, const Sched& S, const Epi& E) {
;     ...
;         if (!has_next) break;
;         if (!keep) {
; #pragma unroll
;         for (int a = 0; a < 2; ++a)
; #pragma unroll
;             for (int b = 0; b < 2; ++b)
; #pragma unroll
;                 for (int m = 0; m < 4; ++m)
; #pragma unroll
;                     for (int n = 0; n < 2; ++n) acc[a][b][m][n] = (f32x4){0.f, 0.f, 0.f, 0.f};
;         }
;         cur = nxt; cA = nA; cB = nB; ++ui;
;         if constexpr (ALIGN_EPI) { if (wr == 1) PG8_BAR; }
;     __device__ __forceinline__ bool operator()(f32x4 (&acc)[2][2][4][2], const pg8::Unit& u, int wr, int wc, int fr, int fq) const {
;     ...
;             for (int m = 0; m < 4; ++m) {
;                 const int row = row0 + ai * 128 + m * 16; const float r = rr[ai * 4 + m];
;                 float o[8];
; #pragma unroll
;                 for (int n = 0; n < 2; ++n)
; #pragma unroll
;                     for (int j = 0; j < 4; ++j) { const float gv = acc[ai][0][m][n][j] * r, uv = acc[ai][1][m][n][j] * r; o[n * 4 + j] = gv * sigmoidf_(gv) * uv; }
;                 u32x4 w; w.x = pk2(o[0], o[1]); w.y = pk2(o[2], o[3]); w.z = pk2(o[4], o[5]); w.w = pk2(o[6], o[7]);
;                 *(u32x4*)(act + (size_t)row * FF + col0) = w;
	v_pk_mul_f32 v[68:69], v[68:69], v[72:73]
	v_cvt_pk_bf16_f32 v78, v74, v75
	v_cvt_pk_bf16_f32 v79, v76, v77
	v_cvt_pk_bf16_f32 v80, v66, v67
	v_cvt_pk_bf16_f32 v81, v68, v69
	global_store_dwordx4 v[156:157], v[78:81], off
	s_mov_b32 s4, 0xdc000
	v_lshl_add_u64 v[156:157], v[156:157], 0, s[4:5]
	s_mov_b32 s4, 0x2c000
	v_mul_f32_e32 v150, 0xbfb8aa3b, v146
	v_mul_f32_e32 v152, v146, v146
	v_pk_mul_f32 v[62:63], v[62:63], v[150:151] op_sel_hi:[1,0]
	v_pk_mul_f32 v[64:65], v[64:65], v[150:151] op_sel_hi:[1,0]
	v_pk_mul_f32 v[54:55], v[54:55], v[150:151] op_sel_hi:[1,0]
	v_pk_mul_f32 v[56:57], v[56:57], v[150:151] op_sel_hi:[1,0]
	v_exp_f32_e32 v62, v62
	v_exp_f32_e32 v63, v63
	v_exp_f32_e32 v64, v64
	v_exp_f32_e32 v65, v65
	v_exp_f32_e32 v54, v54
	v_exp_f32_e32 v55, v55
	v_exp_f32_e32 v56, v56
	v_exp_f32_e32 v57, v57
	v_pk_mul_f32 v[58:59], v[58:59], v[152:153] op_sel_hi:[1,0]
	v_pk_mul_f32 v[60:61], v[60:61], v[152:153] op_sel_hi:[1,0]
	v_pk_mul_f32 v[50:51], v[50:51], v[152:153] op_sel_hi:[1,0]
	v_pk_mul_f32 v[52:53], v[52:53], v[152:153] op_sel_hi:[1,0]
	v_pk_add_f32 v[62:63], v[62:63], v[140:141]
	v_pk_add_f32 v[64:65], v[64:65], v[140:141]
	v_pk_add_f32 v[54:55], v[54:55], v[140:141]
	v_pk_add_f32 v[56:57], v[56:57], v[140:141]
	v_rcp_f32_e32 v62, v62
	v_rcp_f32_e32 v63, v63
	v_rcp_f32_e32 v64, v64
	v_rcp_f32_e32 v65, v65
	v_rcp_f32_e32 v54, v54
	v_rcp_f32_e32 v55, v55
	v_rcp_f32_e32 v56, v56
	v_rcp_f32_e32 v57, v57
	s_nop 0
	v_pk_mul_f32 v[58:59], v[58:59], v[62:63]
	v_pk_mul_f32 v[60:61], v[60:61], v[64:65]
	v_pk_mul_f32 v[50:51], v[50:51], v[54:55]
	v_pk_mul_f32 v[52:53], v[52:53], v[56:57]
	v_cvt_pk_bf16_f32 v62, v58, v59
	v_cvt_pk_bf16_f32 v63, v60, v61
	v_cvt_pk_bf16_f32 v64, v50, v51
	v_cvt_pk_bf16_f32 v65, v52, v53
	global_store_dwordx4 v[156:157], v[62:65], off
	v_lshl_add_u64 v[156:157], v[156:157], 0, s[4:5]
	v_mul_f32_e32 v150, 0xbfb8aa3b, v148
	v_mul_f32_e32 v152, v148, v148
	v_pk_mul_f32 v[46:47], v[46:47], v[150:151] op_sel_hi:[1,0]
	v_pk_mul_f32 v[48:49], v[48:49], v[150:151] op_sel_hi:[1,0]
	v_pk_mul_f32 v[38:39], v[38:39], v[150:151] op_sel_hi:[1,0]
	v_pk_mul_f32 v[40:41], v[40:41], v[150:151] op_sel_hi:[1,0]
	v_exp_f32_e32 v46, v46
	v_exp_f32_e32 v47, v47
	v_exp_f32_e32 v48, v48
	v_exp_f32_e32 v49, v49
	v_exp_f32_e32 v38, v38
	v_exp_f32_e32 v39, v39
	v_exp_f32_e32 v40, v40
	v_exp_f32_e32 v41, v41
	v_pk_mul_f32 v[42:43], v[42:43], v[152:153] op_sel_hi:[1,0]
	v_pk_mul_f32 v[44:45], v[44:45], v[152:153] op_sel_hi:[1,0]
	v_pk_mul_f32 v[34:35], v[34:35], v[152:153] op_sel_hi:[1,0]
	v_pk_mul_f32 v[36:37], v[36:37], v[152:153] op_sel_hi:[1,0]
	v_pk_add_f32 v[46:47], v[46:47], v[140:141]
	v_pk_add_f32 v[48:49], v[48:49], v[140:141]
	v_pk_add_f32 v[38:39], v[38:39], v[140:141]
	v_pk_add_f32 v[40:41], v[40:41], v[140:141]
	v_rcp_f32_e32 v46, v46
	v_rcp_f32_e32 v47, v47
	v_rcp_f32_e32 v48, v48
	v_rcp_f32_e32 v49, v49
	v_rcp_f32_e32 v38, v38
	v_rcp_f32_e32 v39, v39
	v_rcp_f32_e32 v40, v40
	v_rcp_f32_e32 v41, v41
	s_nop 0
	v_pk_mul_f32 v[42:43], v[42:43], v[46:47]
	v_pk_mul_f32 v[44:45], v[44:45], v[48:49]
	v_pk_mul_f32 v[34:35], v[34:35], v[38:39]
	v_pk_mul_f32 v[36:37], v[36:37], v[40:41]
	v_cvt_pk_bf16_f32 v46, v42, v43
	v_cvt_pk_bf16_f32 v47, v44, v45
	v_cvt_pk_bf16_f32 v48, v34, v35
	v_cvt_pk_bf16_f32 v49, v36, v37
	global_store_dwordx4 v[156:157], v[46:49], off
	v_lshl_add_u64 v[156:157], v[156:157], 0, s[4:5]
	v_mul_f32_e32 v150, 0xbfb8aa3b, v144
	v_mul_f32_e32 v152, v144, v144
	v_pk_mul_f32 v[30:31], v[30:31], v[150:151] op_sel_hi:[1,0]
	v_pk_mul_f32 v[32:33], v[32:33], v[150:151] op_sel_hi:[1,0]
	v_pk_mul_f32 v[22:23], v[22:23], v[150:151] op_sel_hi:[1,0]
	v_pk_mul_f32 v[24:25], v[24:25], v[150:151] op_sel_hi:[1,0]
	v_exp_f32_e32 v30, v30
	v_exp_f32_e32 v31, v31
	v_exp_f32_e32 v32, v32
	v_exp_f32_e32 v33, v33
	v_exp_f32_e32 v22, v22
	v_exp_f32_e32 v23, v23
	v_exp_f32_e32 v24, v24
	v_exp_f32_e32 v25, v25
	v_pk_mul_f32 v[26:27], v[26:27], v[152:153] op_sel_hi:[1,0]
	v_pk_mul_f32 v[28:29], v[28:29], v[152:153] op_sel_hi:[1,0]
	v_pk_mul_f32 v[18:19], v[18:19], v[152:153] op_sel_hi:[1,0]
	v_pk_mul_f32 v[20:21], v[20:21], v[152:153] op_sel_hi:[1,0]
	v_pk_add_f32 v[30:31], v[30:31], v[140:141]
	v_pk_add_f32 v[32:33], v[32:33], v[140:141]
	v_pk_add_f32 v[22:23], v[22:23], v[140:141]
	v_pk_add_f32 v[24:25], v[24:25], v[140:141]
	v_rcp_f32_e32 v30, v30
	v_rcp_f32_e32 v31, v31
	v_rcp_f32_e32 v32, v32
	v_rcp_f32_e32 v33, v33
	v_rcp_f32_e32 v22, v22
	v_rcp_f32_e32 v23, v23
	v_rcp_f32_e32 v24, v24
	v_rcp_f32_e32 v25, v25
	s_nop 0
	v_pk_mul_f32 v[26:27], v[26:27], v[30:31]
	v_pk_mul_f32 v[28:29], v[28:29], v[32:33]
	v_pk_mul_f32 v[18:19], v[18:19], v[22:23]
	v_pk_mul_f32 v[20:21], v[20:21], v[24:25]
	v_cvt_pk_bf16_f32 v30, v26, v27
	v_cvt_pk_bf16_f32 v31, v28, v29
	v_cvt_pk_bf16_f32 v32, v18, v19
	v_cvt_pk_bf16_f32 v33, v20, v21
	global_store_dwordx4 v[156:157], v[30:33], off
	v_lshl_add_u64 v[156:157], v[156:157], 0, s[4:5]
	v_mul_f32_e32 v150, 0xbfb8aa3b, v142
	v_mul_f32_e32 v152, v142, v142
	v_pk_mul_f32 v[14:15], v[14:15], v[150:151] op_sel_hi:[1,0]
	v_pk_mul_f32 v[16:17], v[16:17], v[150:151] op_sel_hi:[1,0]
	v_pk_mul_f32 v[6:7], v[6:7], v[150:151] op_sel_hi:[1,0]
	v_pk_mul_f32 v[8:9], v[8:9], v[150:151] op_sel_hi:[1,0]
	v_exp_f32_e32 v14, v14
	v_exp_f32_e32 v15, v15
	v_exp_f32_e32 v16, v16
	v_exp_f32_e32 v17, v17
	v_exp_f32_e32 v6, v6
	v_exp_f32_e32 v7, v7
	v_exp_f32_e32 v8, v8
	v_exp_f32_e32 v9, v9
	v_pk_mul_f32 v[10:11], v[10:11], v[152:153] op_sel_hi:[1,0]
	v_pk_mul_f32 v[12:13], v[12:13], v[152:153] op_sel_hi:[1,0]
	v_pk_mul_f32 v[2:3], v[2:3], v[152:153] op_sel_hi:[1,0]
	v_pk_mul_f32 v[4:5], v[4:5], v[152:153] op_sel_hi:[1,0]
	v_pk_add_f32 v[14:15], v[14:15], v[140:141]
	v_pk_add_f32 v[16:17], v[16:17], v[140:141]
	v_pk_add_f32 v[6:7], v[6:7], v[140:141]
	v_pk_add_f32 v[8:9], v[8:9], v[140:141]
	v_rcp_f32_e32 v14, v14
	v_rcp_f32_e32 v15, v15
	v_rcp_f32_e32 v16, v16
	v_rcp_f32_e32 v17, v17
	v_rcp_f32_e32 v6, v6
	v_rcp_f32_e32 v7, v7
	v_rcp_f32_e32 v8, v8
	v_rcp_f32_e32 v9, v9
	s_nop 0
	v_pk_mul_f32 v[10:11], v[10:11], v[14:15]
	v_pk_mul_f32 v[12:13], v[12:13], v[16:17]
	v_pk_mul_f32 v[2:3], v[2:3], v[6:7]
	v_pk_mul_f32 v[4:5], v[4:5], v[8:9]
	v_cvt_pk_bf16_f32 v14, v10, v11
	v_cvt_pk_bf16_f32 v15, v12, v13
	v_cvt_pk_bf16_f32 v16, v2, v3
	v_cvt_pk_bf16_f32 v17, v4, v5
	global_store_dwordx4 v[156:157], v[14:17], off
	s_mov_b64 s[4:5], -1
	s_andn2_b64 vcc, exec, s[8:9]
	s_cbranch_vccnz .LBB0_867
	s_andn2_b64 vcc, exec, s[10:11]
	s_cbranch_vccnz .LBB0_866
	s_barrier
	s_branch .LBB0_866
